# attention group start: the wait before the ring-reuse barrier no longer drains vmcnt (Q loads and the previous group's stores stay in flight; in-order vmcnt covers them at the first counted wait)
# speedup vs baseline: 1.0078x; 1.0028x over previous
.LBB0_692:
	s_lshl_b32 s9, s12, 8
	s_lshl_b64 s[10:11], s[10:11], 1
	s_add_u32 s22, s13, s10
	s_addc_u32 s23, s23, s11
	s_lshl_b32 s12, s8, 5
	s_and_b64 s[10:11], s[66:67], exec
	s_cselect_b32 s10, 64, s12
	s_cselect_b32 s11, 0, 0
	s_add_u32 s10, s6, s10
	s_mov_b32 m0, s20
	s_waitcnt lgkmcnt(0)
	s_barrier
	s_addc_u32 s11, s7, s11
	s_add_i32 s24, s20, 0x2000
	global_load_lds_dwordx4 v2, s[6:7]
	s_mov_b32 m0, s24
	s_lshl_b32 s12, s8, 6
	global_load_lds_dwordx4 v2, s[10:11]
	s_and_b64 s[10:11], s[66:67], exec
	s_cselect_b32 s10, 0x80, s12
	s_cselect_b32 s11, 0, 0
	s_add_u32 s10, s6, s10
	s_addc_u32 s11, s7, s11
	s_add_i32 s25, s20, 0x4000
	s_mov_b32 m0, s25
	v_mov_b32_e32 v46, v3
	global_load_lds_dwordx4 v2, s[10:11]
	v_mov_b32_e32 v47, v3
	v_mov_b32_e32 v48, v3
	v_mov_b32_e32 v49, v3
	v_mov_b32_e32 v122, 0
	v_mov_b64_e32 v[52:53], v[48:49]
	v_mov_b64_e32 v[56:57], v[48:49]
	v_mov_b64_e32 v[60:61], v[48:49]
	v_mov_b64_e32 v[64:65], v[48:49]
	v_mov_b64_e32 v[68:69], v[48:49]
	v_mov_b64_e32 v[72:73], v[48:49]
	v_mov_b64_e32 v[76:77], v[48:49]
	v_mov_b64_e32 v[80:81], v[48:49]
	v_mov_b64_e32 v[84:85], v[48:49]
	v_mov_b64_e32 v[88:89], v[48:49]
	v_mov_b64_e32 v[92:93], v[48:49]
	v_mov_b64_e32 v[100:101], v[48:49]
	v_mov_b64_e32 v[108:109], v[48:49]
	v_mov_b64_e32 v[112:113], v[48:49]
	v_mov_b64_e32 v[116:117], v[48:49]
	v_mov_b64_e32 v[42:43], v[46:47]
	s_mov_b32 s26, 0
	s_mov_b64 s[10:11], -1
	s_movk_i32 s27, 0x6000
	s_movk_i32 s42, 0x60
	v_mov_b64_e32 v[50:51], v[46:47]
	v_mov_b64_e32 v[54:55], v[46:47]
	v_mov_b64_e32 v[58:59], v[46:47]
	v_mov_b64_e32 v[62:63], v[46:47]
	v_mov_b64_e32 v[66:67], v[46:47]
	v_mov_b64_e32 v[70:71], v[46:47]
	v_mov_b64_e32 v[74:75], v[46:47]
	v_mov_b64_e32 v[78:79], v[46:47]
	v_mov_b64_e32 v[82:83], v[46:47]
	v_mov_b64_e32 v[86:87], v[46:47]
	v_mov_b64_e32 v[90:91], v[46:47]
	v_mov_b64_e32 v[98:99], v[46:47]
	v_mov_b64_e32 v[106:107], v[46:47]
	v_mov_b64_e32 v[110:111], v[46:47]
	v_mov_b64_e32 v[114:115], v[46:47]
	v_mov_b64_e32 v[44:45], v[48:49]
	v_mov_b32_e32 v123, v122
	v_mov_b32_e32 v124, v122
	v_mov_b32_e32 v125, v122
	v_mov_b32_e32 v118, v122
	v_mov_b32_e32 v119, v122
	v_mov_b32_e32 v120, v122
	v_mov_b32_e32 v121, v122
	v_mov_b32_e32 v102, v122
	v_mov_b32_e32 v103, v122
	v_mov_b32_e32 v104, v122
	v_mov_b32_e32 v105, v122
	v_mov_b32_e32 v94, v122
	v_mov_b32_e32 v95, v122
	v_mov_b32_e32 v96, v122
	v_mov_b32_e32 v97, v122
	s_waitcnt vmcnt(0)
	s_branch .LBB0_694

.LBB0_795:
	s_lshl_b64 s[14:15], s[54:55], 1
	s_add_u32 s19, s52, s14
	s_addc_u32 s71, s53, s15
	s_lshl_b64 s[14:15], s[26:27], 1
	s_add_u32 s22, s22, s14
	s_addc_u32 s23, s23, s15
	s_lshl_b64 s[14:15], s[50:51], 1
	s_add_u32 s50, s12, s14
	s_addc_u32 s51, s13, s15
	s_add_i32 s90, s39, 0x2000
	s_add_i32 s96, s39, 0x4000
	s_lshl_b64 s[12:13], s[10:11], 5
	s_and_b64 s[14:15], s[36:37], exec
	s_mov_b32 m0, s39
	s_waitcnt lgkmcnt(0)
	s_barrier
	s_cselect_b32 s12, 64, s12
	global_load_lds_dwordx4 v2, s[64:65]
	s_mov_b32 m0, s90
	s_cselect_b32 s13, 0, s13
	s_add_u32 s12, s64, s12
	global_load_lds_dwordx4 v124, s[16:17]
	s_mov_b32 m0, s96
	s_addc_u32 s13, s65, s13
	s_add_i32 s97, s39, 0x6000
	global_load_lds_dwordx4 v126, s[24:25]
	s_mov_b32 m0, s97
	v_mov_b32_e32 v52, v3
	global_load_lds_dwordx4 v2, s[12:13]
	s_lshl_b64 s[12:13], s[20:21], 5
	s_and_b64 s[14:15], s[74:75], exec
	s_cselect_b32 s12, 64, s12
	s_cselect_b32 s13, 0, s13
	s_add_u32 s12, s16, s12
	s_addc_u32 s13, s17, s13
	s_add_i32 s82, s39, 0x8000
	s_mov_b32 m0, s82
	v_mov_b32_e32 v53, v3
	global_load_lds_dwordx4 v124, s[12:13]
	s_lshl_b64 s[12:13], s[44:45], 5
	s_and_b64 s[14:15], s[86:87], exec
	s_cselect_b32 s12, 64, s12
	s_cselect_b32 s13, 0, s13
	s_add_u32 s12, s24, s12
	s_addc_u32 s13, s25, s13
	s_add_i32 s83, s39, 0xa000
	s_mov_b32 m0, s83
	v_mov_b32_e32 v50, v3
	global_load_lds_dwordx4 v126, s[12:13]
	s_lshl_b64 s[12:13], s[10:11], 6
	s_and_b64 s[14:15], s[36:37], exec
	s_cselect_b32 s12, 0x80, s12
	s_cselect_b32 s13, 0, s13
	s_add_u32 s12, s64, s12
	s_addc_u32 s13, s65, s13
	s_add_i32 s56, s39, 0xc000
	s_mov_b32 m0, s56
	v_mov_b32_e32 v51, v3
	global_load_lds_dwordx4 v2, s[12:13]
	s_lshl_b64 s[12:13], s[20:21], 6
	s_and_b64 s[14:15], s[74:75], exec
	s_cselect_b32 s12, 0x80, s12
	s_cselect_b32 s13, 0, s13
	s_add_u32 s12, s16, s12
	s_addc_u32 s13, s17, s13
	s_add_i32 s57, s39, 0xe000
	s_mov_b32 m0, s57
	v_mov_b32_e32 v119, 0
	global_load_lds_dwordx4 v124, s[12:13]
	s_lshl_b64 s[12:13], s[44:45], 6
	s_and_b64 s[14:15], s[86:87], exec
	s_cselect_b32 s12, 0x80, s12
	s_cselect_b32 s13, 0, s13
	s_add_u32 s12, s24, s12
	s_addc_u32 s13, s25, s13
	s_mov_b32 m0, s92
	v_mov_b64_e32 v[84:85], v[52:53]
	global_load_lds_dwordx4 v126, s[12:13]
	s_waitcnt vmcnt(6)
	s_barrier
	ds_read_b128 v[34:37], v150
	ds_read_b128 v[38:41], v150 offset:1024
	v_readlane_b32 s12, v251, 3
	v_readlane_b32 s14, v251, 5
	v_readlane_b32 s15, v251, 6
	v_readlane_b32 s13, v251, 4
	ds_read_b128 v[46:49], v150 offset:2048
	v_mov_b64_e32 v[44:45], s[14:15]
	v_mov_b64_e32 v[42:43], s[12:13]
	v_mov_b32_e32 v125, v3
	v_mov_b32_e32 v127, v3
	s_waitcnt vmcnt(0) lgkmcnt(0)
	v_mfma_f32_16x16x32_bf16 v[34:37], v[34:37], v[10:13], v[42:45]
	s_mov_b32 s35, 6
	s_mov_b64 s[12:13], -1
	v_mov_b64_e32 v[82:83], v[50:51]
	v_mfma_f32_16x16x32_bf16 v[34:37], v[38:41], v[14:17], v[34:37]
	ds_read_b128 v[38:41], v150 offset:3072
	v_mov_b32_e32 v78, 0
	v_mov_b32_e32 v79, v119
	v_mfma_f32_16x16x32_bf16 v[34:37], v[46:49], v[18:21], v[34:37]
	ds_read_b128 v[46:49], v150 offset:4096
	v_mov_b32_e32 v80, v119
	v_mov_b32_e32 v81, v119
	s_waitcnt lgkmcnt(1)
	v_mfma_f32_16x16x32_bf16 v[34:37], v[38:41], v[22:25], v[34:37]
	ds_read_b128 v[38:41], v150 offset:5120
	v_mov_b32_e32 v74, 0
	v_mov_b32_e32 v75, v119
	s_waitcnt lgkmcnt(1)
	v_mfma_f32_16x16x32_bf16 v[34:37], v[46:49], v[26:29], v[34:37]
	ds_read_b128 v[46:49], v150 offset:6144
	v_mov_b32_e32 v76, v119
	v_mov_b32_e32 v77, v119
	s_waitcnt lgkmcnt(1)
	v_mfma_f32_16x16x32_bf16 v[34:37], v[38:41], v[30:33], v[34:37]
	ds_read_b128 v[38:41], v150 offset:7168
	v_mov_b32_e32 v70, 0
	v_mov_b32_e32 v71, v119
	s_waitcnt lgkmcnt(1)
	v_mfma_f32_16x16x32_bf16 v[42:45], v[46:49], v[10:13], v[42:45]
	ds_read_b128 v[46:49], v150 offset:8192
	v_mov_b32_e32 v72, v119
	v_mov_b32_e32 v73, v119
	s_waitcnt lgkmcnt(1)
	v_mfma_f32_16x16x32_bf16 v[38:41], v[38:41], v[14:17], v[42:45]
	v_mov_b32_e32 v66, 0
	s_nop 1
	ds_read_b128 v[42:45], v150 offset:9216
	v_mov_b32_e32 v67, v119
	s_waitcnt lgkmcnt(1)
	v_mfma_f32_16x16x32_bf16 v[38:41], v[46:49], v[18:21], v[38:41]
	ds_read_b128 v[46:49], v150 offset:10240
	v_mov_b32_e32 v68, v119
	v_mov_b32_e32 v69, v119
	s_waitcnt lgkmcnt(1)
	v_mfma_f32_16x16x32_bf16 v[38:41], v[42:45], v[22:25], v[38:41]
	ds_read_b128 v[42:45], v150 offset:11264
	v_mov_b32_e32 v62, 0
	v_mov_b32_e32 v63, v119
	s_waitcnt lgkmcnt(1)
	v_mfma_f32_16x16x32_bf16 v[38:41], v[46:49], v[26:29], v[38:41]
	v_mov_b32_e32 v64, v119
	v_mov_b32_e32 v65, v119
	v_mov_b32_e32 v58, 0
	s_waitcnt lgkmcnt(0)
	v_mfma_f32_16x16x32_bf16 v[38:41], v[42:45], v[30:33], v[38:41]
	v_mov_b32_e32 v59, v119
	v_mov_b32_e32 v60, v119
	v_mov_b32_e32 v61, v119
	v_mov_b32_e32 v54, 0
	v_mov_b32_e32 v55, v119
	v_mov_b32_e32 v56, v119
	v_mov_b32_e32 v57, v119
	s_branch .LBB0_797

.LBB0_829:
	s_ashr_i32 s10, s20, 4
	s_ashr_i32 s11, s10, 31
	s_bfe_u32 s21, s20, 0x20002
	s_lshl_b64 s[12:13], s[10:11], 8
	s_lshl_b64 s[10:11], s[10:11], 17
	s_add_u32 s10, s38, s10
	s_addc_u32 s11, s39, s11
	s_lshl_b32 s23, s21, 6
	s_lshl_b32 s24, s21, 7
	s_add_u32 s24, s10, s24
	s_addc_u32 s25, s11, 0
	s_or_b32 s10, s12, s23
	s_lshl_b32 s23, s20, 6
	s_lshl_b32 s26, s20, 7
	s_and_b32 s23, s23, 0x80
	s_lshl_b32 s21, s21, 8
	s_and_b32 s26, s26, 0x80
	s_mov_b32 s11, s13
	s_or_b32 s21, s21, s26
	v_add_u32_e32 v2, s23, v1
	s_lshl_b64 s[10:11], s[10:11], 9
	v_lshl_add_u64 v[4:5], s[12:13], 0, v[2:3]
	s_lshl_b32 s12, s21, 1
	s_add_u32 s12, s60, s12
	s_addc_u32 s13, s61, 0
	v_lshlrev_b64 v[8:9], 11, v[4:5]
	v_lshl_add_u64 v[8:9], s[12:13], 0, v[8:9]
	s_add_u32 s12, s24, s42
	s_addc_u32 s13, s25, s43
	v_mov_b32_e32 v135, v3
	s_add_u32 s23, s15, s10
	v_lshl_add_u64 v[8:9], v[8:9], 0, v[134:135]
	s_addc_u32 s24, s16, s11
	global_load_dwordx4 v[10:13], v[8:9], off
	global_load_dwordx4 v[14:17], v[8:9], off offset:128
	s_waitcnt lgkmcnt(0)
	global_load_dwordx4 v[18:21], v[8:9], off offset:64
	global_load_dwordx4 v[22:25], v[8:9], off offset:192
	s_and_b64 s[10:11], s[50:51], exec
	s_cselect_b32 s10, s23, s12
	s_cselect_b32 s11, s24, s13
	s_add_u32 s12, s10, s17
	s_addc_u32 s13, s11, 0
	s_add_i32 s23, s22, 0x2000
	s_mov_b32 m0, s22
	s_waitcnt lgkmcnt(0)
	s_barrier
	v_lshl_add_u64 v[140:141], s[10:11], 0, v[138:139]
	s_add_u32 s10, s10, s18
	global_load_lds_dwordx4 v[140:141], off
	v_lshl_add_u64 v[8:9], s[12:13], 0, v[138:139]
	s_mov_b32 m0, s23
	s_addc_u32 s11, s11, 0
	s_add_i32 s26, s22, 0x4000
	global_load_lds_dwordx4 v[8:9], off
	v_lshl_add_u64 v[8:9], s[10:11], 0, v[138:139]
	s_mov_b32 m0, s26
	v_readlane_b32 s52, v251, 3
	global_load_lds_dwordx4 v[8:9], off
	s_waitcnt vmcnt(2)
	s_barrier
	ds_read_b128 v[26:29], v150
	ds_read_b128 v[30:33], v150 offset:2048
	ds_read_b128 v[42:45], v150 offset:1024
	ds_read_b128 v[46:49], v150 offset:3072
	v_readlane_b32 s53, v251, 4
	v_readlane_b32 s54, v251, 5
	v_readlane_b32 s55, v251, 6
	v_mov_b64_e32 v[34:35], s[52:53]
	v_mov_b32_e32 v74, 0
	v_mov_b64_e32 v[36:37], s[54:55]
	v_mov_b32_e32 v2, v3
	v_mov_b32_e32 v50, v3
	v_mov_b32_e32 v51, v3
	v_mov_b32_e32 v52, v3
	v_mov_b32_e32 v53, v3
	s_movk_i32 s12, 0x60
	s_mov_b64 s[10:11], -1
	v_mov_b32_e32 v75, v74
	v_mov_b32_e32 v76, v74
	v_mov_b32_e32 v77, v74
	v_mov_b32_e32 v86, v74
	v_mov_b32_e32 v87, v74
	v_mov_b32_e32 v88, v74
	v_mov_b32_e32 v89, v74
	v_mov_b32_e32 v78, v74
	v_mov_b32_e32 v79, v74
	v_mov_b32_e32 v80, v74
	v_mov_b64_e32 v[142:143], v[2:3]
	v_lshl_add_u64 v[144:145], v[140:141], 0, s[6:7]
	v_lshl_add_u64 v[146:147], v[140:141], 0, s[8:9]
	s_waitcnt vmcnt(0) lgkmcnt(0)
	v_mfma_f32_16x16x32_bf16 v[38:41], v[26:29], v[10:13], v[34:37]
	v_lshl_add_u64 v[148:149], v[140:141], 0, s[36:37]
	v_mov_b32_e32 v81, v74
	v_mov_b32_e32 v82, v74
	v_mfma_f32_16x16x32_bf16 v[54:57], v[30:33], v[10:13], v[34:37]
	v_mov_b32_e32 v83, v74
	v_mov_b32_e32 v84, v74
	v_mov_b32_e32 v85, v74
	v_mfma_f32_16x16x32_bf16 v[26:29], v[26:29], v[14:17], v[34:37]
	v_mov_b32_e32 v62, v74
	v_mov_b32_e32 v63, v74
	v_mov_b32_e32 v64, v74
	v_mfma_f32_16x16x32_bf16 v[30:33], v[30:33], v[14:17], v[34:37]
	v_mov_b32_e32 v65, v74
	v_mov_b32_e32 v58, v74
	v_mov_b32_e32 v59, v74
	v_mfma_f32_16x16x32_bf16 v[34:37], v[42:45], v[18:21], v[38:41]
	v_mov_b32_e32 v60, v74
	v_mov_b32_e32 v61, v74
	v_mov_b32_e32 v94, v74
	v_mfma_f32_16x16x32_bf16 v[38:41], v[46:49], v[18:21], v[54:57]
	v_mov_b32_e32 v95, v74
	v_mov_b32_e32 v96, v74
	v_mov_b32_e32 v97, v74
	v_mfma_f32_16x16x32_bf16 v[26:29], v[42:45], v[22:25], v[26:29]
	v_mov_b32_e32 v54, v74
	v_mov_b32_e32 v55, v74
	v_mov_b32_e32 v56, v74
	v_mfma_f32_16x16x32_bf16 v[30:33], v[46:49], v[22:25], v[30:33]
	v_mov_b32_e32 v57, v74
	v_mov_b32_e32 v90, v74
	v_mov_b32_e32 v91, v74
	v_mov_b32_e32 v92, v74
	v_mov_b32_e32 v93, v74
	s_branch .LBB0_831

.LBB0_893:
	s_lshl_b64 s[50:51], s[10:11], 5
	s_waitcnt lgkmcnt(0)
	s_barrier
	s_mov_b32 m0, s22
	s_and_b64 s[52:53], s[8:9], exec
	global_load_lds_dwordx4 v2, s[24:25]
	s_mov_b32 m0, s23
	s_cselect_b32 s33, 64, s50
	global_load_lds_dwordx4 v4, s[12:13]
	s_mov_b32 m0, s26
	s_cselect_b32 s19, 0, s51
	s_add_u32 s50, s24, s33
	global_load_lds_dwordx4 v8, s[14:15]
	s_addc_u32 s51, s25, s19
	s_mov_b32 m0, s27
	v_lshl_add_u64 v[120:121], s[24:25], 0, v[2:3]
	global_load_lds_dwordx4 v2, s[50:51]
	s_lshl_b64 s[50:51], s[16:17], 5
	s_and_b64 s[52:53], s[48:49], exec
	s_cselect_b32 s33, 64, s50
	s_cselect_b32 s19, 0, s51
	s_add_u32 s50, s12, s33
	s_addc_u32 s51, s13, s19
	s_add_i32 s19, s22, 0x8000
	s_mov_b32 m0, s19
	v_mov_b32_e32 v5, v3
	global_load_lds_dwordx4 v4, s[50:51]
	s_lshl_b64 s[50:51], s[20:21], 5
	s_and_b64 s[52:53], s[60:61], exec
	s_cselect_b32 s35, 64, s50
	s_cselect_b32 s33, 0, s51
	s_add_u32 s50, s14, s35
	s_addc_u32 s51, s15, s33
	s_add_i32 s35, s22, 0xa000
	s_mov_b32 m0, s35
	v_lshl_add_u64 v[122:123], s[12:13], 0, v[4:5]
	global_load_lds_dwordx4 v8, s[50:51]
	s_lshl_b64 s[50:51], s[10:11], 6
	s_and_b64 s[52:53], s[8:9], exec
	s_cselect_b32 s50, 0x80, s50
	s_cselect_b32 s33, 0, s51
	s_add_u32 s24, s24, s50
	s_addc_u32 s25, s25, s33
	s_add_i32 s86, s22, 0xc000
	s_mov_b32 m0, s86
	v_mov_b32_e32 v9, v3
	global_load_lds_dwordx4 v2, s[24:25]
	s_lshl_b64 s[24:25], s[16:17], 6
	s_and_b64 s[50:51], s[48:49], exec
	s_cselect_b32 s24, 0x80, s24
	s_cselect_b32 s25, 0, s25
	s_add_u32 s12, s12, s24
	s_addc_u32 s13, s13, s25
	s_add_i32 s87, s22, 0xe000
	s_mov_b32 m0, s87
	v_lshl_add_u64 v[124:125], s[14:15], 0, v[8:9]
	global_load_lds_dwordx4 v4, s[12:13]
	s_lshl_b64 s[12:13], s[20:21], 6
	s_and_b64 s[24:25], s[60:61], exec
	s_cselect_b32 s12, 0x80, s12
	s_cselect_b32 s13, 0, s13
	s_add_u32 s12, s14, s12
	s_addc_u32 s13, s15, s13
	s_mov_b32 m0, s47
	v_mov_b32_e32 v4, v3
	global_load_lds_dwordx4 v8, s[12:13]
	v_readlane_b32 s12, v251, 3
	v_readlane_b32 s14, v251, 5
	v_readlane_b32 s15, v251, 6
	s_waitcnt vmcnt(6)
	s_barrier
	v_readlane_b32 s13, v251, 4
	v_mov_b64_e32 v[84:85], s[14:15]
	ds_read_b128 v[34:37], v150
	ds_read_b128 v[38:41], v150 offset:1024
	ds_read_b128 v[42:45], v150 offset:2048
	ds_read_b128 v[46:49], v150 offset:3072
	ds_read_b128 v[50:53], v150 offset:4096
	ds_read_b128 v[54:57], v150 offset:5120
	ds_read_b128 v[58:61], v150 offset:6144
	ds_read_b128 v[62:65], v150 offset:7168
	ds_read_b128 v[66:69], v150 offset:8192
	ds_read_b128 v[70:73], v150 offset:9216
	ds_read_b128 v[74:77], v150 offset:10240
	ds_read_b128 v[78:81], v150 offset:11264
	v_mov_b64_e32 v[82:83], s[12:13]
	s_lshl_b64 s[12:13], s[10:11], 7
	s_and_b64 s[14:15], s[8:9], exec
	s_waitcnt vmcnt(0) lgkmcnt(0)
	v_mfma_f32_16x16x32_bf16 v[34:37], v[34:37], v[10:13], v[82:85]
	s_cselect_b32 s13, 0, s13
	s_cselect_b32 s12, 0x100, s12
	v_lshl_add_u64 v[126:127], v[120:121], 0, s[12:13]
	v_mfma_f32_16x16x32_bf16 v[34:37], v[38:41], v[14:17], v[34:37]
	s_lshl_b64 s[12:13], s[16:17], 7
	s_and_b64 s[14:15], s[48:49], exec
	s_cselect_b32 s13, 0, s13
	v_mfma_f32_16x16x32_bf16 v[38:41], v[58:61], v[10:13], v[82:85]
	s_cselect_b32 s12, 0x100, s12
	v_lshl_add_u64 v[128:129], v[122:123], 0, s[12:13]
	s_lshl_b64 s[12:13], s[20:21], 7
	v_mfma_f32_16x16x32_bf16 v[38:41], v[62:65], v[14:17], v[38:41]
	s_and_b64 s[14:15], s[60:61], exec
	s_cselect_b32 s13, 0, s13
	s_cselect_b32 s12, 0x100, s12
	v_mfma_f32_16x16x32_bf16 v[34:37], v[42:45], v[18:21], v[34:37]
	v_lshl_add_u64 v[130:131], v[124:125], 0, s[12:13]
	s_mul_i32 s11, s10, 0xa0
	s_and_b64 s[12:13], s[8:9], exec
	v_mfma_f32_16x16x32_bf16 v[38:41], v[66:69], v[18:21], v[38:41]
	s_cselect_b32 s13, 0, 0
	s_cselect_b32 s12, 0x140, s11
	v_lshl_add_u64 v[132:133], v[120:121], 0, s[12:13]
	v_mfma_f32_16x16x32_bf16 v[34:37], v[46:49], v[22:25], v[34:37]
	s_mul_i32 s11, s16, 0xa0
	s_and_b64 s[12:13], s[48:49], exec
	s_cselect_b32 s13, 0, 0
	v_mfma_f32_16x16x32_bf16 v[38:41], v[70:73], v[22:25], v[38:41]
	s_cselect_b32 s12, 0x140, s11
	v_lshl_add_u64 v[138:139], v[122:123], 0, s[12:13]
	s_mul_i32 s11, s20, 0xa0
	s_and_b64 s[12:13], s[60:61], exec
	v_mfma_f32_16x16x32_bf16 v[34:37], v[50:53], v[26:29], v[34:37]
	s_cselect_b32 s13, 0, 0
	s_cselect_b32 s12, 0x140, s11
	v_lshl_add_u64 v[140:141], v[124:125], 0, s[12:13]
	v_mfma_f32_16x16x32_bf16 v[38:41], v[74:77], v[26:29], v[38:41]
	s_mul_i32 s11, s10, 0xc0
	s_and_b64 s[12:13], s[8:9], exec
	s_cselect_b32 s13, 0, 0
	s_cselect_b32 s12, 0x180, s11
	v_lshl_add_u64 v[142:143], v[120:121], 0, s[12:13]
	s_mul_i32 s11, s16, 0xc0
	s_and_b64 s[12:13], s[48:49], exec
	v_mfma_f32_16x16x32_bf16 v[34:37], v[54:57], v[30:33], v[34:37]
	s_cselect_b32 s13, 0, 0
	s_cselect_b32 s12, 0x180, s11
	v_lshl_add_u64 v[144:145], v[122:123], 0, s[12:13]
	v_mfma_f32_16x16x32_bf16 v[38:41], v[78:81], v[30:33], v[38:41]
	s_mul_i32 s11, s20, 0xc0
	s_and_b64 s[12:13], s[60:61], exec
	s_cselect_b32 s13, 0, 0
	s_cselect_b32 s12, 0x180, s11
	v_mov_b32_e32 v2, v3
	v_mov_b32_e32 v135, 0
	v_mov_b64_e32 v[52:53], v[4:5]
	v_mov_b64_e32 v[84:85], v[4:5]
	v_lshl_add_u64 v[146:147], v[124:125], 0, s[12:13]
	s_movk_i32 s11, 0x60
	s_mov_b64 s[24:25], -1
	v_mov_b64_e32 v[50:51], v[2:3]
	v_mov_b64_e32 v[82:83], v[2:3]
	v_mov_b32_e32 v78, 0
	v_mov_b32_e32 v79, v135
	v_mov_b32_e32 v80, v135
	v_mov_b32_e32 v81, v135
	v_mov_b32_e32 v74, 0
	v_mov_b32_e32 v75, v135
	v_mov_b32_e32 v76, v135
	v_mov_b32_e32 v77, v135
	v_mov_b32_e32 v70, 0
	v_mov_b32_e32 v71, v135
	v_mov_b32_e32 v72, v135
	v_mov_b32_e32 v73, v135
	v_mov_b32_e32 v66, 0
	v_mov_b32_e32 v67, v135
	v_mov_b32_e32 v68, v135
	v_mov_b32_e32 v69, v135
	v_mov_b32_e32 v62, 0
	v_mov_b32_e32 v63, v135
	v_mov_b32_e32 v64, v135
	v_mov_b32_e32 v65, v135
	v_mov_b32_e32 v58, 0
	v_mov_b32_e32 v59, v135
	v_mov_b32_e32 v60, v135
	v_mov_b32_e32 v61, v135
	v_mov_b32_e32 v54, 0
	v_mov_b32_e32 v55, v135
	v_mov_b32_e32 v56, v135
	v_mov_b32_e32 v57, v135
	s_branch .LBB0_895

.LBB0_1242:
	s_waitcnt lgkmcnt(0)
	s_barrier
	s_lshl_b32 s17, s15, 8
	s_mov_b64 s[12:13], -1
	s_and_b64 vcc, exec, s[36:37]
	s_cbranch_vccz .LBB0_1244
	s_or_b32 s16, s97, s17
	s_mul_i32 s10, s88, s16
	s_mov_b32 s11, s91
	s_mov_b64 s[12:13], 0

.LBB0_1348:
	s_ashr_i32 s10, s25, 4
	s_ashr_i32 s11, s10, 31
	s_lshl_b64 s[12:13], s[10:11], 8
	s_lshl_b64 s[10:11], s[10:11], 19
	s_add_u32 s27, s14, s10
	s_addc_u32 s33, s15, s11
	s_lshl_b32 s26, s25, 6
	s_and_b32 s26, s26, 0x3c0
	s_lshl_b32 s35, s26, 1
	s_add_u32 s27, s27, s35
	s_addc_u32 s33, s33, 0
	s_add_u32 s10, s16, s10
	s_addc_u32 s11, s17, s11
	s_lshl_b32 s38, s26, 9
	s_add_u32 s38, s10, s38
	s_addc_u32 s39, s11, 0
	v_lshl_add_u64 v[136:137], s[12:13], 0, v[130:131]
	s_add_u32 s10, s20, s35
	s_addc_u32 s11, s21, 0
	v_lshlrev_b64 v[8:9], 11, v[136:137]
	v_or_b32_e32 v134, 16, v136
	v_mov_b32_e32 v135, v137
	v_lshl_add_u64 v[8:9], s[10:11], 0, v[8:9]
	v_lshlrev_b64 v[14:15], 11, v[134:135]
	s_add_u32 s12, s27, s42
	v_lshl_add_u64 v[8:9], v[8:9], 0, v[2:3]
	v_lshl_add_u64 v[14:15], s[10:11], 0, v[14:15]
	s_addc_u32 s13, s33, s43
	global_load_dwordx4 v[10:13], v[8:9], off
	s_waitcnt lgkmcnt(0)
	v_lshl_add_u64 v[22:23], v[14:15], 0, v[2:3]
	s_add_u32 s27, s38, s54
	global_load_dwordx4 v[14:17], v[22:23], off
	global_load_dwordx4 v[18:21], v[8:9], off offset:64
	s_addc_u32 s33, s39, s55
	s_and_b64 s[10:11], s[48:49], exec
	s_cselect_b32 s10, s27, s12
	global_load_dwordx4 v[22:25], v[22:23], off offset:64
	s_cselect_b32 s11, s33, s13
	s_add_u32 s12, s10, s19
	s_addc_u32 s13, s11, 0
	s_add_i32 s27, s24, 0x2000
	s_mov_b32 m0, s24
	s_waitcnt lgkmcnt(0)
	s_barrier
	v_lshl_add_u64 v[138:139], s[10:11], 0, v[132:133]
	s_add_u32 s10, s10, s22
	global_load_lds_dwordx4 v[138:139], off
	v_lshl_add_u64 v[8:9], s[12:13], 0, v[132:133]
	s_mov_b32 m0, s27
	s_addc_u32 s11, s11, 0
	s_add_i32 s38, s24, 0x4000
	global_load_lds_dwordx4 v[8:9], off
	v_lshl_add_u64 v[8:9], s[10:11], 0, v[132:133]
	s_mov_b32 m0, s38
	v_add_u32_e32 v5, 0, v148
	global_load_lds_dwordx4 v[8:9], off
	s_waitcnt vmcnt(2)
	s_barrier
	ds_read_b128 v[30:33], v5
	ds_read_b128 v[42:45], v5 offset:1024
	ds_read_b128 v[34:37], v5 offset:2048
	ds_read_b128 v[46:49], v5 offset:3072
	v_readlane_b32 s56, v251, 3
	v_readlane_b32 s57, v251, 4
	v_readlane_b32 s58, v251, 5
	v_readlane_b32 s59, v251, 6
	v_mov_b64_e32 v[26:27], s[56:57]
	v_mov_b32_e32 v74, 0
	v_mov_b64_e32 v[28:29], s[58:59]
	v_mov_b32_e32 v140, v3
	v_mov_b32_e32 v1, v3
	v_mov_b32_e32 v50, v3
	v_mov_b32_e32 v51, v3
	v_mov_b32_e32 v52, v3
	v_mov_b32_e32 v53, v3
	s_movk_i32 s12, 0x60
	s_mov_b64 s[10:11], -1
	v_mov_b32_e32 v75, v74
	v_mov_b32_e32 v76, v74
	v_mov_b32_e32 v77, v74
	v_mov_b32_e32 v90, v74
	v_mov_b32_e32 v91, v74
	v_mov_b32_e32 v92, v74
	v_mov_b32_e32 v93, v74
	v_mov_b32_e32 v82, v74
	v_mov_b32_e32 v83, v74
	v_mov_b32_e32 v84, v74
	v_mov_b32_e32 v85, v74
	v_mov_b32_e32 v78, v74
	v_mov_b32_e32 v79, v74
	v_mov_b32_e32 v80, v74
	v_lshl_add_u64 v[142:143], v[138:139], 0, s[6:7]
	s_waitcnt vmcnt(0) lgkmcnt(0)
	v_mfma_f32_16x16x32_bf16 v[58:61], v[34:37], v[14:17], v[26:29]
	v_lshl_add_u64 v[144:145], v[138:139], 0, s[8:9]
	v_lshl_add_u64 v[146:147], v[138:139], 0, s[36:37]
	v_mov_b32_e32 v81, v74
	v_mfma_f32_16x16x32_bf16 v[38:41], v[30:33], v[10:13], v[26:29]
	v_mov_b32_e32 v70, v74
	v_mov_b32_e32 v71, v74
	v_mov_b32_e32 v72, v74
	v_mfma_f32_16x16x32_bf16 v[54:57], v[34:37], v[10:13], v[26:29]
	v_mov_b32_e32 v73, v74
	v_mov_b32_e32 v66, v74
	v_mov_b32_e32 v67, v74
	v_mfma_f32_16x16x32_bf16 v[30:33], v[30:33], v[14:17], v[26:29]
	v_mov_b32_e32 v68, v74
	v_mov_b32_e32 v69, v74
	v_mov_b32_e32 v62, v74
	v_mfma_f32_16x16x32_bf16 v[34:37], v[42:45], v[18:21], v[38:41]
	v_mov_b32_e32 v63, v74
	v_mov_b32_e32 v64, v74
	v_mov_b32_e32 v65, v74
	v_mfma_f32_16x16x32_bf16 v[38:41], v[46:49], v[18:21], v[54:57]
	v_mov_b32_e32 v94, v74
	v_mov_b32_e32 v95, v74
	v_mov_b32_e32 v96, v74
	v_mfma_f32_16x16x32_bf16 v[26:29], v[42:45], v[22:25], v[30:33]
	v_mov_b32_e32 v97, v74
	v_mov_b32_e32 v86, v74
	v_mov_b32_e32 v87, v74
	v_mfma_f32_16x16x32_bf16 v[30:33], v[46:49], v[22:25], v[58:61]
	v_mov_b32_e32 v88, v74
	v_mov_b32_e32 v89, v74
	s_branch .LBB0_1350
